# GEMM idle-tail weight-copy pulls reduced from 5 (G1) / 3 (G3) to 3 / 2 items per idle workgroup (the rest is taken by the AW phase's non-scan workgroups); on top of PW walk prefetch
# baseline (speedup 1.0000x reference)
.LBB0_406:
	v_readlane_b32 s0, v255, 2
	s_cmp_eq_u32 s0, 3
	v_readlane_b32 s1, v255, 3
	s_cbranch_scc1 .LBB0_469
	v_readlane_b32 s0, v253, 48
	v_readlane_b32 s1, v253, 49
	s_andn2_b64 vcc, exec, s[0:1]
	s_cbranch_vccnz .LBB0_469
	v_readlane_b32 s0, v255, 2
	v_readlane_b32 s8, v250, 5
	v_readlane_b32 s1, v255, 3
	v_mov_b32_e32 v2, v0
	v_readlane_b32 s9, v250, 6
	v_readlane_b32 s10, v250, 7
	v_readlane_b32 s11, v250, 8
	v_readlane_b32 s14, v250, 11
	v_readlane_b32 s15, v250, 12
	v_readlane_b32 s16, v250, 13
	v_readlane_b32 s17, v250, 14
	v_readlane_b32 s18, v250, 15
	v_readlane_b32 s19, v250, 16
	s_add_i32 s0, s0, 1
	s_cmp_eq_u32 s0, 1
	s_cselect_b32 s0, 0, s0
	v_readlane_b32 s12, v250, 9
	v_readfirstlane_b32 s1, v2
	v_readlane_b32 s13, v250, 10
	s_mov_b64 s[10:11], s[14:15]
	s_mov_b64 s[4:5], s[18:19]
	s_mov_b64 s[2:3], s[62:63]
	s_mov_b64 s[8:9], s[16:17]
	v_cmp_eq_u32_e32 vcc, 0, v2
	v_readlane_b32 s20, v250, 17
	v_readlane_b32 s21, v250, 18
	v_readlane_b32 s22, v250, 19
	v_readlane_b32 s23, v250, 20
	s_waitcnt vmcnt(0)
	s_barrier
	s_and_saveexec_b64 s[12:13], vcc
	s_cbranch_execz .LBB0_412
	s_mov_b64 s[16:17], exec
	v_mbcnt_lo_u32_b32 v3, s16, 0
	v_mbcnt_hi_u32_b32 v3, s17, v3
	v_cmp_eq_u32_e32 vcc, 0, v3
	s_and_saveexec_b64 s[14:15], vcc
	s_cbranch_execz .LBB0_411
	s_lshl_b32 s28, s0, 6
	s_lshl_b64 s[18:19], s[28:29], 2
	v_readlane_b32 s20, v252, 11
	s_add_u32 s18, s20, s18
	v_readlane_b32 s20, v252, 12
	s_addc_u32 s19, s20, s19
	v_readlane_b32 s20, v255, 2
	s_cmp_eq_u32 s20, 0
	s_cselect_b32 s20, 0x80, 0
	s_add_u32 s18, s18, s20
	s_addc_u32 s19, s19, 0
	s_bcnt1_i32_b64 s16, s[16:17]
	v_readlane_b32 s20, v255, 2
	s_cmp_eq_u32 s20, 0
	s_cselect_b32 s20, 13, 3
	s_mul_i32 s16, s16, s20
	s_waitcnt lgkmcnt(1)
	v_mov_b32_e32 v4, s16
	global_atomic_add v4, v67, v4, s[18:19] sc0
.LBB0_411:
	s_or_b64 exec, exec, s[14:15]
	s_waitcnt vmcnt(0) lgkmcnt(1)
	v_readfirstlane_b32 s14, v4
	s_nop 1
	v_mad_u32_u24 v3, v3, 3, s14
	v_readlane_b32 s14, v254, 19
	s_nop 1
	v_mov_b32_e32 v4, s14
	ds_write_b32 v4, v3
.LBB0_412:
	s_or_b64 exec, exec, s[12:13]
	v_readlane_b32 s12, v254, 19
	s_waitcnt lgkmcnt(0)
	s_barrier
	v_mov_b32_e32 v3, s12
	ds_read_b32 v3, v3
	s_waitcnt lgkmcnt(0)
	v_readfirstlane_b32 s25, v3
	v_readlane_b32 s12, v255, 2
	s_cmp_eq_u32 s12, 0
	s_cselect_b32 s12, 0x600, 0
	s_add_i32 s25, s25, s12
	s_cmpk_gt_i32 s25, 0xc3f
	s_cbranch_scc1 .LBB0_468
	s_ashr_i32 s14, s1, 6
	s_mul_i32 s16, s0, 0x2c00000
	s_mul_hi_u32 s17, s0, 0x2c00000
	s_add_u32 s4, s4, s16
	s_addc_u32 s5, s5, s17
	s_mul_i32 s13, s0, 0x5800000
	s_mov_b32 s1, s29
	s_mul_hi_u32 s12, s0, 0x5800000
	s_add_u32 s8, s8, s13
	s_addc_u32 s9, s9, s12
	s_lshl_b64 s[12:13], s[0:1], 24
	s_add_u32 s10, s10, s12
	s_addc_u32 s11, s11, s13
	s_mul_i32 s12, s0, 0x3000000
	v_bfe_u32 v3, v2, 5, 1
	s_mul_hi_u32 s13, s0, 0x3000000
	s_add_u32 s12, s2, s12
	s_addc_u32 s13, s3, s13
	v_lshlrev_b32_e32 v5, 1, v3
	s_lshl_b32 s2, s14, 3
	v_lshlrev_b32_e32 v3, 2, v3
	v_and_b32_e32 v4, 31, v2
	v_or_b32_e32 v6, s2, v3
	v_bfe_u32 v7, v2, 4, 2
	v_lshlrev_b32_e32 v8, 4, v2
	v_lshlrev_b32_e32 v2, 3, v2
	v_lshl_or_b32 v52, s14, 2, v5
	v_lshlrev_b32_e32 v53, 2, v4
	v_lshlrev_b32_e32 v54, 10, v4
	v_lshlrev_b32_e32 v5, 3, v4
	v_and_b32_e32 v4, 0x78, v2
	v_add_u32_e32 v2, 64, v6
	s_lshl_b32 s3, s14, 4
	v_bitop3_b32 v56, s2, v5, v3 bitop3:0x36
	v_xor_b32_e32 v57, v2, v5
	v_add_u32_e32 v2, 0x80, v6
	s_lshl_b32 s2, s14, 5
	v_mov_b32_e32 v3, 0xf0
	v_xor_b32_e32 v58, v2, v5
	v_add_u32_e32 v2, 0xc0, v6
	v_bitop3_b32 v61, s2, v3, v8 bitop3:0x48
	s_or_b32 s2, s3, 8
	v_xor_b32_e32 v59, v2, v5
	v_or_b32_e32 v2, s2, v7
	s_lshl_b32 s2, s2, 1
	s_sub_i32 s18, 0xc40, s25
	v_bitop3_b32 v63, s2, v3, v8 bitop3:0x48
	s_or_b32 s2, s3, 12
	v_readlane_b32 s51, v255, 2
	s_cmp_eq_u32 s51, 0
	s_cselect_b32 s51, 13, 3
	s_min_i32 s51, s18, s51
	v_lshlrev_b32_e32 v62, 8, v2
	v_or_b32_e32 v2, s2, v7
	s_lshl_b32 s2, s2, 1
	s_mul_i32 s14, s0, 0x1600000
	s_max_i32 s22, s51, 1
	v_readlane_b32 s18, v252, 13
	s_mul_hi_u32 s15, s0, 0x1600000
	s_add_u32 s14, s18, s14
	v_readlane_b32 s18, v252, 14
	s_addc_u32 s15, s18, s15
	v_readlane_b32 s18, v252, 15
	s_add_u32 s16, s18, s16
	v_readlane_b32 s18, v252, 16
	v_or_b32_e32 v55, s3, v7
	v_bitop3_b32 v65, s2, v3, v8 bitop3:0x48
	s_mul_hi_u32 s2, s0, 0x1b00000
	s_mul_i32 s3, s0, 0x1b00000
	s_addc_u32 s17, s18, s17
	s_lshl_b64 s[0:1], s[0:1], 23
	v_readlane_b32 s18, v252, 17
	s_add_u32 s18, s18, s0
	v_readlane_b32 s0, v252, 18
	s_addc_u32 s19, s0, s1
	v_readlane_b32 s0, v252, 1
	v_lshlrev_b32_e32 v64, 8, v2
	s_add_u32 s20, s0, s3
	v_readlane_b32 s0, v252, 2
	v_mov_b32_e32 v2, 0
	s_mov_b32 s50, 1
	v_lshlrev_b32_e32 v60, 8, v55
	s_addc_u32 s21, s0, s2
	s_lshl_b32 s52, s22, 3
	s_lshl_b32 s53, s25, 7
	s_lshl_b32 s54, s25, 3
	s_mov_b64 s[22:23], 0
	s_mov_b32 s55, 0
	v_lshlrev_b32_e32 v66, 1, v4
	s_mov_b32 s56, 0
	v_mov_b32_e32 v3, v2
	v_mov_b32_e32 v4, v2
	v_mov_b32_e32 v5, v2
	v_mov_b32_e32 v10, v2
	v_mov_b32_e32 v11, v2
	v_mov_b32_e32 v12, v2
	v_mov_b32_e32 v13, v2
	v_mov_b32_e32 v18, v2
	v_mov_b32_e32 v19, v2
	v_mov_b32_e32 v20, v2
	v_mov_b32_e32 v21, v2
	v_mov_b32_e32 v26, v2
	v_mov_b32_e32 v27, v2
	v_mov_b32_e32 v28, v2
	v_mov_b32_e32 v29, v2
	v_mov_b32_e32 v6, v2
	v_mov_b32_e32 v7, v2
	v_mov_b32_e32 v8, v2
	v_mov_b32_e32 v9, v2
	v_mov_b32_e32 v14, v2
	v_mov_b32_e32 v15, v2
	v_mov_b32_e32 v16, v2
	v_mov_b32_e32 v17, v2
	v_mov_b32_e32 v22, v2
	v_mov_b32_e32 v23, v2
	v_mov_b32_e32 v24, v2
	v_mov_b32_e32 v25, v2
	v_mov_b32_e32 v30, v2
	v_mov_b32_e32 v31, v2
	v_mov_b32_e32 v32, v2
	v_mov_b32_e32 v33, v2
	s_branch .LBB0_415

.LBB0_1630:
	v_readlane_b32 s0, v255, 2
	s_cmp_eq_u32 s0, 3
	v_readlane_b32 s1, v255, 3
	s_cbranch_scc1 .LBB0_1693
	v_readlane_b32 s0, v253, 59
	v_readlane_b32 s1, v253, 60
	s_andn2_b64 vcc, exec, s[0:1]
	s_cbranch_vccnz .LBB0_1693
	v_readlane_b32 s0, v255, 2
	v_readlane_b32 s4, v250, 5
	v_readlane_b32 s1, v255, 3
	v_mov_b32_e32 v2, v0
	v_readlane_b32 s5, v250, 6
	v_readlane_b32 s6, v250, 7
	v_readlane_b32 s7, v250, 8
	v_readlane_b32 s8, v250, 9
	v_readlane_b32 s9, v250, 10
	v_readlane_b32 s10, v250, 11
	v_readlane_b32 s11, v250, 12
	v_readlane_b32 s12, v250, 13
	v_readlane_b32 s13, v250, 14
	v_readlane_b32 s14, v250, 15
	v_readlane_b32 s15, v250, 16
	s_add_i32 s0, s0, 1
	s_mov_b64 s[8:9], s[10:11]
	v_readfirstlane_b32 s1, v2
	s_mov_b64 s[4:5], s[14:15]
	s_mov_b64 s[2:3], s[62:63]
	s_mov_b64 s[6:7], s[12:13]
	v_cmp_eq_u32_e32 vcc, 0, v2
	v_readlane_b32 s16, v250, 17
	v_readlane_b32 s17, v250, 18
	v_readlane_b32 s18, v250, 19
	v_readlane_b32 s19, v250, 20
	s_waitcnt vmcnt(0)
	s_barrier
	s_and_saveexec_b64 s[10:11], vcc
	s_cbranch_execz .LBB0_1636
	s_mov_b64 s[14:15], exec
	v_mbcnt_lo_u32_b32 v3, s14, 0
	v_mbcnt_hi_u32_b32 v3, s15, v3
	v_cmp_eq_u32_e32 vcc, 0, v3
	s_and_saveexec_b64 s[12:13], vcc
	s_cbranch_execz .LBB0_1635
	s_lshl_b32 s28, s0, 6
	s_lshl_b64 s[16:17], s[28:29], 2
	v_readlane_b32 s18, v252, 11
	s_add_u32 s16, s18, s16
	v_readlane_b32 s18, v252, 12
	s_addc_u32 s17, s18, s17
	s_bcnt1_i32_b64 s14, s[14:15]
	s_mul_i32 s14, s14, 2
	v_mov_b32_e32 v4, s14
	global_atomic_add v4, v67, v4, s[16:17] sc0
.LBB0_1635:
	s_or_b64 exec, exec, s[12:13]
	s_waitcnt vmcnt(0)
	v_readfirstlane_b32 s12, v4
	s_nop 1
	v_mad_u32_u24 v3, v3, 2, s12
	v_readlane_b32 s12, v254, 19
	s_nop 1
	v_mov_b32_e32 v4, s12
	ds_write_b32 v4, v3
.LBB0_1636:
	s_or_b64 exec, exec, s[10:11]
	v_readlane_b32 s10, v254, 19
	s_waitcnt lgkmcnt(0)
	s_barrier
	v_mov_b32_e32 v3, s10
	ds_read_b32 v3, v3
	s_waitcnt lgkmcnt(0)
	v_readfirstlane_b32 s25, v3
	s_cmpk_gt_i32 s25, 0xc3f
	s_cbranch_scc1 .LBB0_1692
	s_ashr_i32 s12, s1, 6
	s_mul_i32 s14, s0, 0x2c00000
	s_mul_hi_u32 s15, s0, 0x2c00000
	s_add_u32 s4, s4, s14
	s_addc_u32 s5, s5, s15
	s_mul_i32 s11, s0, 0x5800000
	s_mov_b32 s1, s29
	s_mul_hi_u32 s10, s0, 0x5800000
	s_add_u32 s6, s6, s11
	s_addc_u32 s7, s7, s10
	s_lshl_b64 s[10:11], s[0:1], 24
	s_add_u32 s8, s8, s10
	s_addc_u32 s9, s9, s11
	s_mul_i32 s10, s0, 0x3000000
	v_bfe_u32 v3, v2, 5, 1
	s_mul_hi_u32 s11, s0, 0x3000000
	s_add_u32 s10, s2, s10
	s_addc_u32 s11, s3, s11
	v_lshlrev_b32_e32 v5, 1, v3
	s_lshl_b32 s2, s12, 3
	v_lshlrev_b32_e32 v3, 2, v3
	v_and_b32_e32 v4, 31, v2
	v_or_b32_e32 v6, s2, v3
	v_bfe_u32 v7, v2, 4, 2
	v_lshlrev_b32_e32 v8, 4, v2
	v_lshlrev_b32_e32 v2, 3, v2
	v_lshl_or_b32 v52, s12, 2, v5
	v_lshlrev_b32_e32 v53, 2, v4
	v_lshlrev_b32_e32 v54, 10, v4
	v_lshlrev_b32_e32 v5, 3, v4
	v_and_b32_e32 v4, 0x78, v2
	v_add_u32_e32 v2, 64, v6
	s_lshl_b32 s3, s12, 4
	v_bitop3_b32 v56, s2, v5, v3 bitop3:0x36
	v_xor_b32_e32 v57, v2, v5
	v_add_u32_e32 v2, 0x80, v6
	s_lshl_b32 s2, s12, 5
	v_mov_b32_e32 v3, 0xf0
	v_xor_b32_e32 v58, v2, v5
	v_add_u32_e32 v2, 0xc0, v6
	v_bitop3_b32 v61, s2, v3, v8 bitop3:0x48
	s_or_b32 s2, s3, 8
	v_xor_b32_e32 v59, v2, v5
	v_or_b32_e32 v2, s2, v7
	s_lshl_b32 s2, s2, 1
	s_sub_i32 s16, 0xc40, s25
	v_bitop3_b32 v63, s2, v3, v8 bitop3:0x48
	s_or_b32 s2, s3, 12
	s_min_i32 s51, s16, 2
	v_lshlrev_b32_e32 v62, 8, v2
	v_or_b32_e32 v2, s2, v7
	s_lshl_b32 s2, s2, 1
	s_mul_i32 s12, s0, 0x1600000
	s_max_i32 s20, s51, 1
	v_readlane_b32 s16, v252, 13
	s_mul_hi_u32 s13, s0, 0x1600000
	s_add_u32 s12, s16, s12
	v_readlane_b32 s16, v252, 14
	s_addc_u32 s13, s16, s13
	v_readlane_b32 s16, v252, 15
	s_add_u32 s14, s16, s14
	v_readlane_b32 s16, v252, 16
	v_or_b32_e32 v55, s3, v7
	v_bitop3_b32 v65, s2, v3, v8 bitop3:0x48
	s_mul_hi_u32 s2, s0, 0x1b00000
	s_mul_i32 s3, s0, 0x1b00000
	s_addc_u32 s15, s16, s15
	s_lshl_b64 s[0:1], s[0:1], 23
	v_readlane_b32 s16, v252, 17
	s_add_u32 s16, s16, s0
	v_readlane_b32 s0, v252, 18
	s_addc_u32 s17, s0, s1
	v_readlane_b32 s0, v252, 1
	v_lshlrev_b32_e32 v64, 8, v2
	s_add_u32 s18, s0, s3
	v_readlane_b32 s0, v252, 2
	v_mov_b32_e32 v2, 0
	s_mov_b32 s50, 1
	v_lshlrev_b32_e32 v60, 8, v55
	s_addc_u32 s19, s0, s2
	s_lshl_b32 s52, s20, 3
	s_lshl_b32 s53, s25, 7
	s_lshl_b32 s54, s25, 3
	s_mov_b64 s[22:23], 0
	s_mov_b32 s55, 0
	v_lshlrev_b32_e32 v66, 1, v4
	s_mov_b32 s56, 0
	v_mov_b32_e32 v3, v2
	v_mov_b32_e32 v4, v2
	v_mov_b32_e32 v5, v2
	v_mov_b32_e32 v10, v2
	v_mov_b32_e32 v11, v2
	v_mov_b32_e32 v12, v2
	v_mov_b32_e32 v13, v2
	v_mov_b32_e32 v18, v2
	v_mov_b32_e32 v19, v2
	v_mov_b32_e32 v20, v2
	v_mov_b32_e32 v21, v2
	v_mov_b32_e32 v26, v2
	v_mov_b32_e32 v27, v2
	v_mov_b32_e32 v28, v2
	v_mov_b32_e32 v29, v2
	v_mov_b32_e32 v6, v2
	v_mov_b32_e32 v7, v2
	v_mov_b32_e32 v8, v2
	v_mov_b32_e32 v9, v2
	v_mov_b32_e32 v14, v2
	v_mov_b32_e32 v15, v2
	v_mov_b32_e32 v16, v2
	v_mov_b32_e32 v17, v2
	v_mov_b32_e32 v22, v2
	v_mov_b32_e32 v23, v2
	v_mov_b32_e32 v24, v2
	v_mov_b32_e32 v25, v2
	v_mov_b32_e32 v30, v2
	v_mov_b32_e32 v31, v2
	v_mov_b32_e32 v32, v2
	v_mov_b32_e32 v33, v2
	s_branch .LBB0_1639
